# MoBA routing prologue: cnt[j] fetched by v_readlane from one preloaded vector instead of an LDS read + full wait per iteration (list padding and descriptor-base loops)
# speedup vs baseline: 1.0062x; 1.0012x over previous
.LBB0_372:
	s_or_b64 exec, exec, s[2:3]
	v_cmp_gt_i32_e64 s[40:41], 15, v33
	s_and_b64 s[8:9], s[40:41], s[38:39]
	s_waitcnt lgkmcnt(0)
	s_barrier
	s_and_saveexec_b64 s[2:3], s[8:9]
	s_cbranch_execz .LBB0_378
	v_and_b32_e32 v224, 63, v3
	v_lshlrev_b32_e32 v224, 2, v224
	ds_read_b32 v224, v224 offset:56832
	s_waitcnt lgkmcnt(0)
	s_mov_b32 s14, 0
	s_mov_b32 s15, 0xde00
	s_mov_b32 s16, 0xd600
	s_mov_b64 s[8:9], 0
	s_branch .LBB0_375

.LBB0_375:
	v_readlane_b32 s99, v224, s14
	s_nop 1
	v_mov_b32_e32 v1, s99
	v_cmp_ge_i32_e64 s[38:39], v3, v1
	s_and_saveexec_b64 s[10:11], s[38:39]
	s_cbranch_execz .LBB0_374
	v_add_u32_e32 v1, 15, v1
	v_and_b32_e32 v1, -16, v1
	v_cmp_lt_i32_e64 s[38:39], v3, v1
	s_and_b64 exec, exec, s[38:39]
	s_cbranch_execz .LBB0_374
	v_add_u32_e32 v1, s16, v3
	ds_write_b8 v1, v206
	s_branch .LBB0_374
.LBB0_378:
	s_or_b64 exec, exec, s[2:3]
	v_lshl_add_u32 v21, v34, 1, 2
	v_cmp_lt_i32_e64 s[38:39], v3, v21
	v_lshlrev_b32_e32 v22, 4, v3
	s_and_saveexec_b64 s[2:3], s[38:39]
	v_sub_u32_e32 v9, v0, v19
	v_add_u32_e32 v8, v0, v15
	ds_write_b128 v22, v[8:11] offset:56960
	s_or_b64 exec, exec, s[2:3]
	s_and_saveexec_b64 s[2:3], vcc
	v_readlane_b32 s34, v248, 25
	v_readlane_b32 s35, v248, 26
	s_cbranch_execz .LBB0_398
	v_min_i32_e32 v0, v3, v7
	v_cmp_lt_i32_e32 vcc, 0, v0
	v_mov_b32_e32 v8, v21
	s_and_saveexec_b64 s[8:9], vcc
	s_cbranch_execz .LBB0_385
	s_mov_b32 s99, 0
	s_mov_b32 s14, 0xde00
	s_mov_b64 s[10:11], 0
	v_mov_b32_e32 v8, v21
.LBB0_383:
	v_readlane_b32 s15, v224, s99
	v_add_u32_e32 v0, -1, v0
	s_add_i32 s99, s99, 1
	v_cmp_eq_u32_e32 vcc, 0, v0
	s_nop 0
	s_add_i32 s15, s15, 15
	s_ashr_i32 s15, s15, 4
	s_add_i32 s15, s15, 3
	s_and_b32 s15, s15, -4
	v_add_u32_e32 v8, s15, v8
	s_or_b64 s[10:11], vcc, s[10:11]
	s_andn2_b64 exec, exec, s[10:11]
	s_cbranch_execnz .LBB0_383
	s_or_b64 exec, exec, s[10:11]
